# P0 x->bf16 row-per-wave stream with nt loads (x does not allocate in the memory-side cache while it still holds the launch's dirty lines), on top of the fused P9
# baseline (speedup 1.0000x reference)
; __device__ __forceinline__ unsigned cvtpk(float lo, float hi) { f32x2_t v = {lo, hi}; bf16x2_t b = __builtin_convertvector(v, bf16x2_t); return __builtin_bit_cast(unsigned, b); }
; __global__ void __launch_bounds__(NTHREADS, 2) fwd_megakernel(Args args) {
;     ...
;         const size_t n8 = (size_t)MTOK * DM / 8;
;         for (size_t i = gt; i < n8; i += NGT) { const f32x4 a = *(const f32x4*)(x + i * 8), c = *(const f32x4*)(x + i * 8 + 4);
;             v4u o; o.x = cvtpk(a[0], a[1]); o.y = cvtpk(a[2], a[3]); o.z = cvtpk(c[0], c[1]); o.w = cvtpk(c[2], c[3]); *(v4u*)(XB + i * 8) = o; }
.LBB0_43:
	s_or_b64 exec, exec, s[0:1]
	s_waitcnt lgkmcnt(0)
	s_ashr_i32 s15, s42, 31
	s_mov_b32 s14, s42
	s_mov_b64 s[0:1], 0x800000
	s_lshl_b64 s[24:25], s[14:15], 9
	v_cmp_gt_u64_e32 vcc, s[0:1], v[4:5]
	s_and_saveexec_b64 s[0:1], vcc
	s_cbranch_execz .LBB0_46
	s_cmp_lg_u32 s42, 0x100
	s_cbranch_scc1 .Lxrow_generic
	v_readfirstlane_b32 s4, v178
	s_lshr_b32 s4, s4, 6
	s_lshl_b32 s5, s2, 3
	s_add_i32 s10, s4, s5
	v_mbcnt_lo_u32_b32 v1, -1, 0
	v_mbcnt_hi_u32_b32 v1, -1, v1
	v_lshlrev_b32_e32 v2, 4, v1
	v_add_u32_e32 v3, 0x1000, v2
	v_lshlrev_b32_e32 v16, 3, v1
	s_lshl_b32 s8, s10, 13
	s_add_u32 s4, s12, s8
	s_addc_u32 s5, s13, 0
	s_lshl_b32 s8, s10, 12
	s_add_u32 s8, s40, s8
	s_addc_u32 s9, s41, 0
	s_add_u32 s8, s8, 0x7c00000
	s_addc_u32 s9, s9, 0
	global_load_dwordx4 v[20:23], v2, s[4:5] nt
	global_load_dwordx4 v[24:27], v2, s[4:5] offset:1024 nt
	global_load_dwordx4 v[28:31], v2, s[4:5] offset:2048 nt
	global_load_dwordx4 v[32:35], v2, s[4:5] offset:3072 nt
	global_load_dwordx4 v[36:39], v3, s[4:5] nt
	global_load_dwordx4 v[40:43], v3, s[4:5] offset:1024 nt
	global_load_dwordx4 v[44:47], v3, s[4:5] offset:2048 nt
	global_load_dwordx4 v[48:51], v3, s[4:5] offset:3072 nt
	s_add_u32 s4, s4, 0x1000000
	s_addc_u32 s5, s5, 0
	global_load_dwordx4 v[52:55], v2, s[4:5] nt
	global_load_dwordx4 v[56:59], v2, s[4:5] offset:1024 nt
	global_load_dwordx4 v[60:63], v2, s[4:5] offset:2048 nt
	global_load_dwordx4 v[64:67], v2, s[4:5] offset:3072 nt
	global_load_dwordx4 v[68:71], v3, s[4:5] nt
	global_load_dwordx4 v[72:75], v3, s[4:5] offset:1024 nt
	global_load_dwordx4 v[76:79], v3, s[4:5] offset:2048 nt
	global_load_dwordx4 v[80:83], v3, s[4:5] offset:3072 nt
	s_add_u32 s4, s4, 0x1000000
	s_addc_u32 s5, s5, 0
	s_waitcnt vmcnt(8)
	v_cvt_pk_bf16_f32 v20, v20, v21
	v_cvt_pk_bf16_f32 v21, v22, v23
	v_cvt_pk_bf16_f32 v24, v24, v25
	v_cvt_pk_bf16_f32 v25, v26, v27
	v_cvt_pk_bf16_f32 v28, v28, v29
	v_cvt_pk_bf16_f32 v29, v30, v31
	v_cvt_pk_bf16_f32 v32, v32, v33
	v_cvt_pk_bf16_f32 v33, v34, v35
	v_cvt_pk_bf16_f32 v36, v36, v37
	v_cvt_pk_bf16_f32 v37, v38, v39
	v_cvt_pk_bf16_f32 v40, v40, v41
	v_cvt_pk_bf16_f32 v41, v42, v43
	v_cvt_pk_bf16_f32 v44, v44, v45
	v_cvt_pk_bf16_f32 v45, v46, v47
	v_cvt_pk_bf16_f32 v48, v48, v49
	v_cvt_pk_bf16_f32 v49, v50, v51
	global_store_dwordx2 v16, v[20:21], s[8:9]
	global_store_dwordx2 v16, v[24:25], s[8:9] offset:512
	global_store_dwordx2 v16, v[28:29], s[8:9] offset:1024
	global_store_dwordx2 v16, v[32:33], s[8:9] offset:1536
	global_store_dwordx2 v16, v[36:37], s[8:9] offset:2048
	global_store_dwordx2 v16, v[40:41], s[8:9] offset:2560
	global_store_dwordx2 v16, v[44:45], s[8:9] offset:3072
	global_store_dwordx2 v16, v[48:49], s[8:9] offset:3584
	s_add_u32 s8, s8, 0x800000
	s_addc_u32 s9, s9, 0
	global_load_dwordx4 v[20:23], v2, s[4:5] nt
	global_load_dwordx4 v[24:27], v2, s[4:5] offset:1024 nt
	global_load_dwordx4 v[28:31], v2, s[4:5] offset:2048 nt
	global_load_dwordx4 v[32:35], v2, s[4:5] offset:3072 nt
	global_load_dwordx4 v[36:39], v3, s[4:5] nt
	global_load_dwordx4 v[40:43], v3, s[4:5] offset:1024 nt
	global_load_dwordx4 v[44:47], v3, s[4:5] offset:2048 nt
	global_load_dwordx4 v[48:51], v3, s[4:5] offset:3072 nt
	s_add_u32 s4, s4, 0x1000000
	s_addc_u32 s5, s5, 0
	s_waitcnt vmcnt(16)
	v_cvt_pk_bf16_f32 v52, v52, v53
	v_cvt_pk_bf16_f32 v53, v54, v55
	v_cvt_pk_bf16_f32 v56, v56, v57
	v_cvt_pk_bf16_f32 v57, v58, v59
	v_cvt_pk_bf16_f32 v60, v60, v61
	v_cvt_pk_bf16_f32 v61, v62, v63
	v_cvt_pk_bf16_f32 v64, v64, v65
	v_cvt_pk_bf16_f32 v65, v66, v67
	v_cvt_pk_bf16_f32 v68, v68, v69
	v_cvt_pk_bf16_f32 v69, v70, v71
	v_cvt_pk_bf16_f32 v72, v72, v73
	v_cvt_pk_bf16_f32 v73, v74, v75
	v_cvt_pk_bf16_f32 v76, v76, v77
	v_cvt_pk_bf16_f32 v77, v78, v79
	v_cvt_pk_bf16_f32 v80, v80, v81
	v_cvt_pk_bf16_f32 v81, v82, v83
	global_store_dwordx2 v16, v[52:53], s[8:9]
	global_store_dwordx2 v16, v[56:57], s[8:9] offset:512
	global_store_dwordx2 v16, v[60:61], s[8:9] offset:1024
	global_store_dwordx2 v16, v[64:65], s[8:9] offset:1536
	global_store_dwordx2 v16, v[68:69], s[8:9] offset:2048
	global_store_dwordx2 v16, v[72:73], s[8:9] offset:2560
	global_store_dwordx2 v16, v[76:77], s[8:9] offset:3072
	global_store_dwordx2 v16, v[80:81], s[8:9] offset:3584
	s_add_u32 s8, s8, 0x800000
	s_addc_u32 s9, s9, 0
	global_load_dwordx4 v[52:55], v2, s[4:5] nt
	global_load_dwordx4 v[56:59], v2, s[4:5] offset:1024 nt
	global_load_dwordx4 v[60:63], v2, s[4:5] offset:2048 nt
	global_load_dwordx4 v[64:67], v2, s[4:5] offset:3072 nt
	global_load_dwordx4 v[68:71], v3, s[4:5] nt
	global_load_dwordx4 v[72:75], v3, s[4:5] offset:1024 nt
	global_load_dwordx4 v[76:79], v3, s[4:5] offset:2048 nt
	global_load_dwordx4 v[80:83], v3, s[4:5] offset:3072 nt
	s_add_u32 s4, s4, 0x1000000
	s_addc_u32 s5, s5, 0
	s_waitcnt vmcnt(16)
	v_cvt_pk_bf16_f32 v20, v20, v21
	v_cvt_pk_bf16_f32 v21, v22, v23
	v_cvt_pk_bf16_f32 v24, v24, v25
	v_cvt_pk_bf16_f32 v25, v26, v27
	v_cvt_pk_bf16_f32 v28, v28, v29
	v_cvt_pk_bf16_f32 v29, v30, v31
	v_cvt_pk_bf16_f32 v32, v32, v33
	v_cvt_pk_bf16_f32 v33, v34, v35
	v_cvt_pk_bf16_f32 v36, v36, v37
	v_cvt_pk_bf16_f32 v37, v38, v39
	v_cvt_pk_bf16_f32 v40, v40, v41
	v_cvt_pk_bf16_f32 v41, v42, v43
	v_cvt_pk_bf16_f32 v44, v44, v45
	v_cvt_pk_bf16_f32 v45, v46, v47
	v_cvt_pk_bf16_f32 v48, v48, v49
	v_cvt_pk_bf16_f32 v49, v50, v51
	global_store_dwordx2 v16, v[20:21], s[8:9]
	global_store_dwordx2 v16, v[24:25], s[8:9] offset:512
	global_store_dwordx2 v16, v[28:29], s[8:9] offset:1024
	global_store_dwordx2 v16, v[32:33], s[8:9] offset:1536
	global_store_dwordx2 v16, v[36:37], s[8:9] offset:2048
	global_store_dwordx2 v16, v[40:41], s[8:9] offset:2560
	global_store_dwordx2 v16, v[44:45], s[8:9] offset:3072
	global_store_dwordx2 v16, v[48:49], s[8:9] offset:3584
	s_add_u32 s8, s8, 0x800000
	s_addc_u32 s9, s9, 0
	global_load_dwordx4 v[20:23], v2, s[4:5] nt
	global_load_dwordx4 v[24:27], v2, s[4:5] offset:1024 nt
	global_load_dwordx4 v[28:31], v2, s[4:5] offset:2048 nt
	global_load_dwordx4 v[32:35], v2, s[4:5] offset:3072 nt
	global_load_dwordx4 v[36:39], v3, s[4:5] nt
	global_load_dwordx4 v[40:43], v3, s[4:5] offset:1024 nt
	global_load_dwordx4 v[44:47], v3, s[4:5] offset:2048 nt
	global_load_dwordx4 v[48:51], v3, s[4:5] offset:3072 nt
	s_add_u32 s4, s4, 0x1000000
	s_addc_u32 s5, s5, 0
	s_waitcnt vmcnt(16)
; __device__ __forceinline__ unsigned cvtpk(float lo, float hi) { f32x2_t v = {lo, hi}; bf16x2_t b = __builtin_convertvector(v, bf16x2_t); return __builtin_bit_cast(unsigned, b); }
; __global__ void __launch_bounds__(NTHREADS, 2) fwd_megakernel(Args args) {
;     ...
;         const size_t n8 = (size_t)MTOK * DM / 8;
;         for (size_t i = gt; i < n8; i += NGT) { const f32x4 a = *(const f32x4*)(x + i * 8), c = *(const f32x4*)(x + i * 8 + 4);
;             v4u o; o.x = cvtpk(a[0], a[1]); o.y = cvtpk(a[2], a[3]); o.z = cvtpk(c[0], c[1]); o.w = cvtpk(c[2], c[3]); *(v4u*)(XB + i * 8) = o; }
	v_cvt_pk_bf16_f32 v52, v52, v53
	v_cvt_pk_bf16_f32 v53, v54, v55
	v_cvt_pk_bf16_f32 v56, v56, v57
	v_cvt_pk_bf16_f32 v57, v58, v59
	v_cvt_pk_bf16_f32 v60, v60, v61
	v_cvt_pk_bf16_f32 v61, v62, v63
	v_cvt_pk_bf16_f32 v64, v64, v65
	v_cvt_pk_bf16_f32 v65, v66, v67
	v_cvt_pk_bf16_f32 v68, v68, v69
	v_cvt_pk_bf16_f32 v69, v70, v71
	v_cvt_pk_bf16_f32 v72, v72, v73
	v_cvt_pk_bf16_f32 v73, v74, v75
	v_cvt_pk_bf16_f32 v76, v76, v77
	v_cvt_pk_bf16_f32 v77, v78, v79
	v_cvt_pk_bf16_f32 v80, v80, v81
	v_cvt_pk_bf16_f32 v81, v82, v83
	global_store_dwordx2 v16, v[52:53], s[8:9]
	global_store_dwordx2 v16, v[56:57], s[8:9] offset:512
	global_store_dwordx2 v16, v[60:61], s[8:9] offset:1024
	global_store_dwordx2 v16, v[64:65], s[8:9] offset:1536
	global_store_dwordx2 v16, v[68:69], s[8:9] offset:2048
	global_store_dwordx2 v16, v[72:73], s[8:9] offset:2560
	global_store_dwordx2 v16, v[76:77], s[8:9] offset:3072
	global_store_dwordx2 v16, v[80:81], s[8:9] offset:3584
	s_add_u32 s8, s8, 0x800000
	s_addc_u32 s9, s9, 0
	global_load_dwordx4 v[52:55], v2, s[4:5] nt
	global_load_dwordx4 v[56:59], v2, s[4:5] offset:1024 nt
	global_load_dwordx4 v[60:63], v2, s[4:5] offset:2048 nt
	global_load_dwordx4 v[64:67], v2, s[4:5] offset:3072 nt
	global_load_dwordx4 v[68:71], v3, s[4:5] nt
	global_load_dwordx4 v[72:75], v3, s[4:5] offset:1024 nt
	global_load_dwordx4 v[76:79], v3, s[4:5] offset:2048 nt
	global_load_dwordx4 v[80:83], v3, s[4:5] offset:3072 nt
	s_add_u32 s4, s4, 0x1000000
	s_addc_u32 s5, s5, 0
	s_waitcnt vmcnt(16)
	v_cvt_pk_bf16_f32 v20, v20, v21
	v_cvt_pk_bf16_f32 v21, v22, v23
	v_cvt_pk_bf16_f32 v24, v24, v25
	v_cvt_pk_bf16_f32 v25, v26, v27
	v_cvt_pk_bf16_f32 v28, v28, v29
	v_cvt_pk_bf16_f32 v29, v30, v31
	v_cvt_pk_bf16_f32 v32, v32, v33
	v_cvt_pk_bf16_f32 v33, v34, v35
	v_cvt_pk_bf16_f32 v36, v36, v37
	v_cvt_pk_bf16_f32 v37, v38, v39
	v_cvt_pk_bf16_f32 v40, v40, v41
	v_cvt_pk_bf16_f32 v41, v42, v43
	v_cvt_pk_bf16_f32 v44, v44, v45
	v_cvt_pk_bf16_f32 v45, v46, v47
	v_cvt_pk_bf16_f32 v48, v48, v49
	v_cvt_pk_bf16_f32 v49, v50, v51
	global_store_dwordx2 v16, v[20:21], s[8:9]
	global_store_dwordx2 v16, v[24:25], s[8:9] offset:512
	global_store_dwordx2 v16, v[28:29], s[8:9] offset:1024
	global_store_dwordx2 v16, v[32:33], s[8:9] offset:1536
	global_store_dwordx2 v16, v[36:37], s[8:9] offset:2048
	global_store_dwordx2 v16, v[40:41], s[8:9] offset:2560
	global_store_dwordx2 v16, v[44:45], s[8:9] offset:3072
	global_store_dwordx2 v16, v[48:49], s[8:9] offset:3584
	s_add_u32 s8, s8, 0x800000
	s_addc_u32 s9, s9, 0
	global_load_dwordx4 v[20:23], v2, s[4:5] nt
	global_load_dwordx4 v[24:27], v2, s[4:5] offset:1024 nt
	global_load_dwordx4 v[28:31], v2, s[4:5] offset:2048 nt
	global_load_dwordx4 v[32:35], v2, s[4:5] offset:3072 nt
	global_load_dwordx4 v[36:39], v3, s[4:5] nt
	global_load_dwordx4 v[40:43], v3, s[4:5] offset:1024 nt
	global_load_dwordx4 v[44:47], v3, s[4:5] offset:2048 nt
	global_load_dwordx4 v[48:51], v3, s[4:5] offset:3072 nt
	s_add_u32 s4, s4, 0x1000000
	s_addc_u32 s5, s5, 0
	s_waitcnt vmcnt(16)
	v_cvt_pk_bf16_f32 v52, v52, v53
	v_cvt_pk_bf16_f32 v53, v54, v55
	v_cvt_pk_bf16_f32 v56, v56, v57
	v_cvt_pk_bf16_f32 v57, v58, v59
	v_cvt_pk_bf16_f32 v60, v60, v61
	v_cvt_pk_bf16_f32 v61, v62, v63
	v_cvt_pk_bf16_f32 v64, v64, v65
	v_cvt_pk_bf16_f32 v65, v66, v67
	v_cvt_pk_bf16_f32 v68, v68, v69
	v_cvt_pk_bf16_f32 v69, v70, v71
	v_cvt_pk_bf16_f32 v72, v72, v73
	v_cvt_pk_bf16_f32 v73, v74, v75
	v_cvt_pk_bf16_f32 v76, v76, v77
	v_cvt_pk_bf16_f32 v77, v78, v79
	v_cvt_pk_bf16_f32 v80, v80, v81
	v_cvt_pk_bf16_f32 v81, v82, v83
	global_store_dwordx2 v16, v[52:53], s[8:9]
	global_store_dwordx2 v16, v[56:57], s[8:9] offset:512
	global_store_dwordx2 v16, v[60:61], s[8:9] offset:1024
	global_store_dwordx2 v16, v[64:65], s[8:9] offset:1536
	global_store_dwordx2 v16, v[68:69], s[8:9] offset:2048
	global_store_dwordx2 v16, v[72:73], s[8:9] offset:2560
	global_store_dwordx2 v16, v[76:77], s[8:9] offset:3072
	global_store_dwordx2 v16, v[80:81], s[8:9] offset:3584
	s_add_u32 s8, s8, 0x800000
	s_addc_u32 s9, s9, 0
	global_load_dwordx4 v[52:55], v2, s[4:5] nt
	global_load_dwordx4 v[56:59], v2, s[4:5] offset:1024 nt
	global_load_dwordx4 v[60:63], v2, s[4:5] offset:2048 nt
	global_load_dwordx4 v[64:67], v2, s[4:5] offset:3072 nt
	global_load_dwordx4 v[68:71], v3, s[4:5] nt
	global_load_dwordx4 v[72:75], v3, s[4:5] offset:1024 nt
	global_load_dwordx4 v[76:79], v3, s[4:5] offset:2048 nt
	global_load_dwordx4 v[80:83], v3, s[4:5] offset:3072 nt
	s_add_u32 s4, s4, 0x1000000
	s_addc_u32 s5, s5, 0
	s_waitcnt vmcnt(16)
	v_cvt_pk_bf16_f32 v20, v20, v21
	v_cvt_pk_bf16_f32 v21, v22, v23
	v_cvt_pk_bf16_f32 v24, v24, v25
	v_cvt_pk_bf16_f32 v25, v26, v27
	v_cvt_pk_bf16_f32 v28, v28, v29
	v_cvt_pk_bf16_f32 v29, v30, v31
	v_cvt_pk_bf16_f32 v32, v32, v33
	v_cvt_pk_bf16_f32 v33, v34, v35
	v_cvt_pk_bf16_f32 v36, v36, v37
	v_cvt_pk_bf16_f32 v37, v38, v39
	v_cvt_pk_bf16_f32 v40, v40, v41
	v_cvt_pk_bf16_f32 v41, v42, v43
	v_cvt_pk_bf16_f32 v44, v44, v45
	v_cvt_pk_bf16_f32 v45, v46, v47
	v_cvt_pk_bf16_f32 v48, v48, v49
	v_cvt_pk_bf16_f32 v49, v50, v51
	global_store_dwordx2 v16, v[20:21], s[8:9]
	global_store_dwordx2 v16, v[24:25], s[8:9] offset:512
	global_store_dwordx2 v16, v[28:29], s[8:9] offset:1024
	global_store_dwordx2 v16, v[32:33], s[8:9] offset:1536
	global_store_dwordx2 v16, v[36:37], s[8:9] offset:2048
	global_store_dwordx2 v16, v[40:41], s[8:9] offset:2560
	global_store_dwordx2 v16, v[44:45], s[8:9] offset:3072
	global_store_dwordx2 v16, v[48:49], s[8:9] offset:3584
	s_add_u32 s8, s8, 0x800000
	s_addc_u32 s9, s9, 0
	global_load_dwordx4 v[20:23], v2, s[4:5] nt
	global_load_dwordx4 v[24:27], v2, s[4:5] offset:1024 nt
	global_load_dwordx4 v[28:31], v2, s[4:5] offset:2048 nt
	global_load_dwordx4 v[32:35], v2, s[4:5] offset:3072 nt
	global_load_dwordx4 v[36:39], v3, s[4:5] nt
	global_load_dwordx4 v[40:43], v3, s[4:5] offset:1024 nt
	global_load_dwordx4 v[44:47], v3, s[4:5] offset:2048 nt
	global_load_dwordx4 v[48:51], v3, s[4:5] offset:3072 nt
	s_add_u32 s4, s4, 0x1000000
	s_addc_u32 s5, s5, 0
	s_waitcnt vmcnt(16)
; __device__ __forceinline__ unsigned cvtpk(float lo, float hi) { f32x2_t v = {lo, hi}; bf16x2_t b = __builtin_convertvector(v, bf16x2_t); return __builtin_bit_cast(unsigned, b); }
; __global__ void __launch_bounds__(NTHREADS, 2) fwd_megakernel(Args args) {
;     ...
;         const size_t n8 = (size_t)MTOK * DM / 8;
;         for (size_t i = gt; i < n8; i += NGT) { const f32x4 a = *(const f32x4*)(x + i * 8), c = *(const f32x4*)(x + i * 8 + 4);
;             v4u o; o.x = cvtpk(a[0], a[1]); o.y = cvtpk(a[2], a[3]); o.z = cvtpk(c[0], c[1]); o.w = cvtpk(c[2], c[3]); *(v4u*)(XB + i * 8) = o; }
	v_cvt_pk_bf16_f32 v52, v52, v53
	v_cvt_pk_bf16_f32 v53, v54, v55
	v_cvt_pk_bf16_f32 v56, v56, v57
	v_cvt_pk_bf16_f32 v57, v58, v59
	v_cvt_pk_bf16_f32 v60, v60, v61
	v_cvt_pk_bf16_f32 v61, v62, v63
	v_cvt_pk_bf16_f32 v64, v64, v65
	v_cvt_pk_bf16_f32 v65, v66, v67
	v_cvt_pk_bf16_f32 v68, v68, v69
	v_cvt_pk_bf16_f32 v69, v70, v71
	v_cvt_pk_bf16_f32 v72, v72, v73
	v_cvt_pk_bf16_f32 v73, v74, v75
	v_cvt_pk_bf16_f32 v76, v76, v77
	v_cvt_pk_bf16_f32 v77, v78, v79
	v_cvt_pk_bf16_f32 v80, v80, v81
	v_cvt_pk_bf16_f32 v81, v82, v83
	global_store_dwordx2 v16, v[52:53], s[8:9]
	global_store_dwordx2 v16, v[56:57], s[8:9] offset:512
	global_store_dwordx2 v16, v[60:61], s[8:9] offset:1024
	global_store_dwordx2 v16, v[64:65], s[8:9] offset:1536
	global_store_dwordx2 v16, v[68:69], s[8:9] offset:2048
	global_store_dwordx2 v16, v[72:73], s[8:9] offset:2560
	global_store_dwordx2 v16, v[76:77], s[8:9] offset:3072
	global_store_dwordx2 v16, v[80:81], s[8:9] offset:3584
	s_add_u32 s8, s8, 0x800000
	s_addc_u32 s9, s9, 0
	global_load_dwordx4 v[52:55], v2, s[4:5] nt
	global_load_dwordx4 v[56:59], v2, s[4:5] offset:1024 nt
	global_load_dwordx4 v[60:63], v2, s[4:5] offset:2048 nt
	global_load_dwordx4 v[64:67], v2, s[4:5] offset:3072 nt
	global_load_dwordx4 v[68:71], v3, s[4:5] nt
	global_load_dwordx4 v[72:75], v3, s[4:5] offset:1024 nt
	global_load_dwordx4 v[76:79], v3, s[4:5] offset:2048 nt
	global_load_dwordx4 v[80:83], v3, s[4:5] offset:3072 nt
	s_add_u32 s4, s4, 0x1000000
	s_addc_u32 s5, s5, 0
	s_waitcnt vmcnt(16)
	v_cvt_pk_bf16_f32 v20, v20, v21
	v_cvt_pk_bf16_f32 v21, v22, v23
	v_cvt_pk_bf16_f32 v24, v24, v25
	v_cvt_pk_bf16_f32 v25, v26, v27
	v_cvt_pk_bf16_f32 v28, v28, v29
	v_cvt_pk_bf16_f32 v29, v30, v31
	v_cvt_pk_bf16_f32 v32, v32, v33
	v_cvt_pk_bf16_f32 v33, v34, v35
	v_cvt_pk_bf16_f32 v36, v36, v37
	v_cvt_pk_bf16_f32 v37, v38, v39
	v_cvt_pk_bf16_f32 v40, v40, v41
	v_cvt_pk_bf16_f32 v41, v42, v43
	v_cvt_pk_bf16_f32 v44, v44, v45
	v_cvt_pk_bf16_f32 v45, v46, v47
	v_cvt_pk_bf16_f32 v48, v48, v49
	v_cvt_pk_bf16_f32 v49, v50, v51
	global_store_dwordx2 v16, v[20:21], s[8:9]
	global_store_dwordx2 v16, v[24:25], s[8:9] offset:512
	global_store_dwordx2 v16, v[28:29], s[8:9] offset:1024
	global_store_dwordx2 v16, v[32:33], s[8:9] offset:1536
	global_store_dwordx2 v16, v[36:37], s[8:9] offset:2048
	global_store_dwordx2 v16, v[40:41], s[8:9] offset:2560
	global_store_dwordx2 v16, v[44:45], s[8:9] offset:3072
	global_store_dwordx2 v16, v[48:49], s[8:9] offset:3584
	s_add_u32 s8, s8, 0x800000
	s_addc_u32 s9, s9, 0
	global_load_dwordx4 v[20:23], v2, s[4:5] nt
	global_load_dwordx4 v[24:27], v2, s[4:5] offset:1024 nt
	global_load_dwordx4 v[28:31], v2, s[4:5] offset:2048 nt
	global_load_dwordx4 v[32:35], v2, s[4:5] offset:3072 nt
	global_load_dwordx4 v[36:39], v3, s[4:5] nt
	global_load_dwordx4 v[40:43], v3, s[4:5] offset:1024 nt
	global_load_dwordx4 v[44:47], v3, s[4:5] offset:2048 nt
	global_load_dwordx4 v[48:51], v3, s[4:5] offset:3072 nt
	s_add_u32 s4, s4, 0x1000000
	s_addc_u32 s5, s5, 0
	s_waitcnt vmcnt(16)
	v_cvt_pk_bf16_f32 v52, v52, v53
	v_cvt_pk_bf16_f32 v53, v54, v55
	v_cvt_pk_bf16_f32 v56, v56, v57
	v_cvt_pk_bf16_f32 v57, v58, v59
	v_cvt_pk_bf16_f32 v60, v60, v61
	v_cvt_pk_bf16_f32 v61, v62, v63
	v_cvt_pk_bf16_f32 v64, v64, v65
	v_cvt_pk_bf16_f32 v65, v66, v67
	v_cvt_pk_bf16_f32 v68, v68, v69
	v_cvt_pk_bf16_f32 v69, v70, v71
	v_cvt_pk_bf16_f32 v72, v72, v73
	v_cvt_pk_bf16_f32 v73, v74, v75
	v_cvt_pk_bf16_f32 v76, v76, v77
	v_cvt_pk_bf16_f32 v77, v78, v79
	v_cvt_pk_bf16_f32 v80, v80, v81
	v_cvt_pk_bf16_f32 v81, v82, v83
	global_store_dwordx2 v16, v[52:53], s[8:9]
	global_store_dwordx2 v16, v[56:57], s[8:9] offset:512
	global_store_dwordx2 v16, v[60:61], s[8:9] offset:1024
	global_store_dwordx2 v16, v[64:65], s[8:9] offset:1536
	global_store_dwordx2 v16, v[68:69], s[8:9] offset:2048
	global_store_dwordx2 v16, v[72:73], s[8:9] offset:2560
	global_store_dwordx2 v16, v[76:77], s[8:9] offset:3072
	global_store_dwordx2 v16, v[80:81], s[8:9] offset:3584
	s_add_u32 s8, s8, 0x800000
	s_addc_u32 s9, s9, 0
	global_load_dwordx4 v[52:55], v2, s[4:5] nt
	global_load_dwordx4 v[56:59], v2, s[4:5] offset:1024 nt
	global_load_dwordx4 v[60:63], v2, s[4:5] offset:2048 nt
	global_load_dwordx4 v[64:67], v2, s[4:5] offset:3072 nt
	global_load_dwordx4 v[68:71], v3, s[4:5] nt
	global_load_dwordx4 v[72:75], v3, s[4:5] offset:1024 nt
	global_load_dwordx4 v[76:79], v3, s[4:5] offset:2048 nt
	global_load_dwordx4 v[80:83], v3, s[4:5] offset:3072 nt
	s_add_u32 s4, s4, 0x1000000
	s_addc_u32 s5, s5, 0
	s_waitcnt vmcnt(16)
	v_cvt_pk_bf16_f32 v20, v20, v21
	v_cvt_pk_bf16_f32 v21, v22, v23
	v_cvt_pk_bf16_f32 v24, v24, v25
	v_cvt_pk_bf16_f32 v25, v26, v27
	v_cvt_pk_bf16_f32 v28, v28, v29
	v_cvt_pk_bf16_f32 v29, v30, v31
	v_cvt_pk_bf16_f32 v32, v32, v33
	v_cvt_pk_bf16_f32 v33, v34, v35
	v_cvt_pk_bf16_f32 v36, v36, v37
	v_cvt_pk_bf16_f32 v37, v38, v39
	v_cvt_pk_bf16_f32 v40, v40, v41
	v_cvt_pk_bf16_f32 v41, v42, v43
	v_cvt_pk_bf16_f32 v44, v44, v45
	v_cvt_pk_bf16_f32 v45, v46, v47
	v_cvt_pk_bf16_f32 v48, v48, v49
	v_cvt_pk_bf16_f32 v49, v50, v51
	global_store_dwordx2 v16, v[20:21], s[8:9]
	global_store_dwordx2 v16, v[24:25], s[8:9] offset:512
	global_store_dwordx2 v16, v[28:29], s[8:9] offset:1024
	global_store_dwordx2 v16, v[32:33], s[8:9] offset:1536
	global_store_dwordx2 v16, v[36:37], s[8:9] offset:2048
	global_store_dwordx2 v16, v[40:41], s[8:9] offset:2560
	global_store_dwordx2 v16, v[44:45], s[8:9] offset:3072
	global_store_dwordx2 v16, v[48:49], s[8:9] offset:3584
	s_add_u32 s8, s8, 0x800000
	s_addc_u32 s9, s9, 0
	global_load_dwordx4 v[20:23], v2, s[4:5] nt
	global_load_dwordx4 v[24:27], v2, s[4:5] offset:1024 nt
	global_load_dwordx4 v[28:31], v2, s[4:5] offset:2048 nt
	global_load_dwordx4 v[32:35], v2, s[4:5] offset:3072 nt
	global_load_dwordx4 v[36:39], v3, s[4:5] nt
	global_load_dwordx4 v[40:43], v3, s[4:5] offset:1024 nt
	global_load_dwordx4 v[44:47], v3, s[4:5] offset:2048 nt
	global_load_dwordx4 v[48:51], v3, s[4:5] offset:3072 nt
	s_add_u32 s4, s4, 0x1000000
	s_addc_u32 s5, s5, 0
	s_waitcnt vmcnt(16)
; __device__ __forceinline__ unsigned cvtpk(float lo, float hi) { f32x2_t v = {lo, hi}; bf16x2_t b = __builtin_convertvector(v, bf16x2_t); return __builtin_bit_cast(unsigned, b); }
; __global__ void __launch_bounds__(NTHREADS, 2) fwd_megakernel(Args args) {
;     ...
;         const size_t n8 = (size_t)MTOK * DM / 8;
;         for (size_t i = gt; i < n8; i += NGT) { const f32x4 a = *(const f32x4*)(x + i * 8), c = *(const f32x4*)(x + i * 8 + 4);
;             v4u o; o.x = cvtpk(a[0], a[1]); o.y = cvtpk(a[2], a[3]); o.z = cvtpk(c[0], c[1]); o.w = cvtpk(c[2], c[3]); *(v4u*)(XB + i * 8) = o; }
	v_cvt_pk_bf16_f32 v52, v52, v53
	v_cvt_pk_bf16_f32 v53, v54, v55
	v_cvt_pk_bf16_f32 v56, v56, v57
	v_cvt_pk_bf16_f32 v57, v58, v59
	v_cvt_pk_bf16_f32 v60, v60, v61
	v_cvt_pk_bf16_f32 v61, v62, v63
	v_cvt_pk_bf16_f32 v64, v64, v65
	v_cvt_pk_bf16_f32 v65, v66, v67
	v_cvt_pk_bf16_f32 v68, v68, v69
	v_cvt_pk_bf16_f32 v69, v70, v71
	v_cvt_pk_bf16_f32 v72, v72, v73
	v_cvt_pk_bf16_f32 v73, v74, v75
	v_cvt_pk_bf16_f32 v76, v76, v77
	v_cvt_pk_bf16_f32 v77, v78, v79
	v_cvt_pk_bf16_f32 v80, v80, v81
	v_cvt_pk_bf16_f32 v81, v82, v83
	global_store_dwordx2 v16, v[52:53], s[8:9]
	global_store_dwordx2 v16, v[56:57], s[8:9] offset:512
	global_store_dwordx2 v16, v[60:61], s[8:9] offset:1024
	global_store_dwordx2 v16, v[64:65], s[8:9] offset:1536
	global_store_dwordx2 v16, v[68:69], s[8:9] offset:2048
	global_store_dwordx2 v16, v[72:73], s[8:9] offset:2560
	global_store_dwordx2 v16, v[76:77], s[8:9] offset:3072
	global_store_dwordx2 v16, v[80:81], s[8:9] offset:3584
	s_add_u32 s8, s8, 0x800000
	s_addc_u32 s9, s9, 0
	global_load_dwordx4 v[52:55], v2, s[4:5] nt
	global_load_dwordx4 v[56:59], v2, s[4:5] offset:1024 nt
	global_load_dwordx4 v[60:63], v2, s[4:5] offset:2048 nt
	global_load_dwordx4 v[64:67], v2, s[4:5] offset:3072 nt
	global_load_dwordx4 v[68:71], v3, s[4:5] nt
	global_load_dwordx4 v[72:75], v3, s[4:5] offset:1024 nt
	global_load_dwordx4 v[76:79], v3, s[4:5] offset:2048 nt
	global_load_dwordx4 v[80:83], v3, s[4:5] offset:3072 nt
	s_add_u32 s4, s4, 0x1000000
	s_addc_u32 s5, s5, 0
	s_waitcnt vmcnt(16)
	v_cvt_pk_bf16_f32 v20, v20, v21
	v_cvt_pk_bf16_f32 v21, v22, v23
	v_cvt_pk_bf16_f32 v24, v24, v25
	v_cvt_pk_bf16_f32 v25, v26, v27
	v_cvt_pk_bf16_f32 v28, v28, v29
	v_cvt_pk_bf16_f32 v29, v30, v31
	v_cvt_pk_bf16_f32 v32, v32, v33
	v_cvt_pk_bf16_f32 v33, v34, v35
	v_cvt_pk_bf16_f32 v36, v36, v37
	v_cvt_pk_bf16_f32 v37, v38, v39
	v_cvt_pk_bf16_f32 v40, v40, v41
	v_cvt_pk_bf16_f32 v41, v42, v43
	v_cvt_pk_bf16_f32 v44, v44, v45
	v_cvt_pk_bf16_f32 v45, v46, v47
	v_cvt_pk_bf16_f32 v48, v48, v49
	v_cvt_pk_bf16_f32 v49, v50, v51
	global_store_dwordx2 v16, v[20:21], s[8:9]
	global_store_dwordx2 v16, v[24:25], s[8:9] offset:512
	global_store_dwordx2 v16, v[28:29], s[8:9] offset:1024
	global_store_dwordx2 v16, v[32:33], s[8:9] offset:1536
	global_store_dwordx2 v16, v[36:37], s[8:9] offset:2048
	global_store_dwordx2 v16, v[40:41], s[8:9] offset:2560
	global_store_dwordx2 v16, v[44:45], s[8:9] offset:3072
	global_store_dwordx2 v16, v[48:49], s[8:9] offset:3584
	s_add_u32 s8, s8, 0x800000
	s_addc_u32 s9, s9, 0
	global_load_dwordx4 v[20:23], v2, s[4:5] nt
	global_load_dwordx4 v[24:27], v2, s[4:5] offset:1024 nt
	global_load_dwordx4 v[28:31], v2, s[4:5] offset:2048 nt
	global_load_dwordx4 v[32:35], v2, s[4:5] offset:3072 nt
	global_load_dwordx4 v[36:39], v3, s[4:5] nt
	global_load_dwordx4 v[40:43], v3, s[4:5] offset:1024 nt
	global_load_dwordx4 v[44:47], v3, s[4:5] offset:2048 nt
	global_load_dwordx4 v[48:51], v3, s[4:5] offset:3072 nt
	s_add_u32 s4, s4, 0x1000000
	s_addc_u32 s5, s5, 0
	s_waitcnt vmcnt(16)
	v_cvt_pk_bf16_f32 v52, v52, v53
	v_cvt_pk_bf16_f32 v53, v54, v55
	v_cvt_pk_bf16_f32 v56, v56, v57
	v_cvt_pk_bf16_f32 v57, v58, v59
	v_cvt_pk_bf16_f32 v60, v60, v61
	v_cvt_pk_bf16_f32 v61, v62, v63
	v_cvt_pk_bf16_f32 v64, v64, v65
	v_cvt_pk_bf16_f32 v65, v66, v67
	v_cvt_pk_bf16_f32 v68, v68, v69
	v_cvt_pk_bf16_f32 v69, v70, v71
	v_cvt_pk_bf16_f32 v72, v72, v73
	v_cvt_pk_bf16_f32 v73, v74, v75
	v_cvt_pk_bf16_f32 v76, v76, v77
	v_cvt_pk_bf16_f32 v77, v78, v79
	v_cvt_pk_bf16_f32 v80, v80, v81
	v_cvt_pk_bf16_f32 v81, v82, v83
	global_store_dwordx2 v16, v[52:53], s[8:9]
	global_store_dwordx2 v16, v[56:57], s[8:9] offset:512
	global_store_dwordx2 v16, v[60:61], s[8:9] offset:1024
	global_store_dwordx2 v16, v[64:65], s[8:9] offset:1536
	global_store_dwordx2 v16, v[68:69], s[8:9] offset:2048
	global_store_dwordx2 v16, v[72:73], s[8:9] offset:2560
	global_store_dwordx2 v16, v[76:77], s[8:9] offset:3072
	global_store_dwordx2 v16, v[80:81], s[8:9] offset:3584
	s_add_u32 s8, s8, 0x800000
	s_addc_u32 s9, s9, 0
	global_load_dwordx4 v[52:55], v2, s[4:5] nt
	global_load_dwordx4 v[56:59], v2, s[4:5] offset:1024 nt
	global_load_dwordx4 v[60:63], v2, s[4:5] offset:2048 nt
	global_load_dwordx4 v[64:67], v2, s[4:5] offset:3072 nt
	global_load_dwordx4 v[68:71], v3, s[4:5] nt
	global_load_dwordx4 v[72:75], v3, s[4:5] offset:1024 nt
	global_load_dwordx4 v[76:79], v3, s[4:5] offset:2048 nt
	global_load_dwordx4 v[80:83], v3, s[4:5] offset:3072 nt
	s_add_u32 s4, s4, 0x1000000
	s_addc_u32 s5, s5, 0
	s_waitcnt vmcnt(16)
	v_cvt_pk_bf16_f32 v20, v20, v21
	v_cvt_pk_bf16_f32 v21, v22, v23
	v_cvt_pk_bf16_f32 v24, v24, v25
	v_cvt_pk_bf16_f32 v25, v26, v27
	v_cvt_pk_bf16_f32 v28, v28, v29
	v_cvt_pk_bf16_f32 v29, v30, v31
	v_cvt_pk_bf16_f32 v32, v32, v33
	v_cvt_pk_bf16_f32 v33, v34, v35
	v_cvt_pk_bf16_f32 v36, v36, v37
	v_cvt_pk_bf16_f32 v37, v38, v39
	v_cvt_pk_bf16_f32 v40, v40, v41
	v_cvt_pk_bf16_f32 v41, v42, v43
	v_cvt_pk_bf16_f32 v44, v44, v45
	v_cvt_pk_bf16_f32 v45, v46, v47
	v_cvt_pk_bf16_f32 v48, v48, v49
	v_cvt_pk_bf16_f32 v49, v50, v51
	global_store_dwordx2 v16, v[20:21], s[8:9]
	global_store_dwordx2 v16, v[24:25], s[8:9] offset:512
	global_store_dwordx2 v16, v[28:29], s[8:9] offset:1024
	global_store_dwordx2 v16, v[32:33], s[8:9] offset:1536
	global_store_dwordx2 v16, v[36:37], s[8:9] offset:2048
	global_store_dwordx2 v16, v[40:41], s[8:9] offset:2560
	global_store_dwordx2 v16, v[44:45], s[8:9] offset:3072
	global_store_dwordx2 v16, v[48:49], s[8:9] offset:3584
	s_add_u32 s8, s8, 0x800000
	s_addc_u32 s9, s9, 0
	s_waitcnt vmcnt(8)
	v_cvt_pk_bf16_f32 v52, v52, v53
	v_cvt_pk_bf16_f32 v53, v54, v55
	v_cvt_pk_bf16_f32 v56, v56, v57
	v_cvt_pk_bf16_f32 v57, v58, v59
	v_cvt_pk_bf16_f32 v60, v60, v61
	v_cvt_pk_bf16_f32 v61, v62, v63
	v_cvt_pk_bf16_f32 v64, v64, v65
	v_cvt_pk_bf16_f32 v65, v66, v67
	v_cvt_pk_bf16_f32 v68, v68, v69
	v_cvt_pk_bf16_f32 v69, v70, v71
	v_cvt_pk_bf16_f32 v72, v72, v73
	v_cvt_pk_bf16_f32 v73, v74, v75
	v_cvt_pk_bf16_f32 v76, v76, v77
	v_cvt_pk_bf16_f32 v77, v78, v79
	v_cvt_pk_bf16_f32 v80, v80, v81
	v_cvt_pk_bf16_f32 v81, v82, v83
	global_store_dwordx2 v16, v[52:53], s[8:9]
	global_store_dwordx2 v16, v[56:57], s[8:9] offset:512
	global_store_dwordx2 v16, v[60:61], s[8:9] offset:1024
	global_store_dwordx2 v16, v[64:65], s[8:9] offset:1536
	global_store_dwordx2 v16, v[68:69], s[8:9] offset:2048
	global_store_dwordx2 v16, v[72:73], s[8:9] offset:2560
	global_store_dwordx2 v16, v[76:77], s[8:9] offset:3072
	global_store_dwordx2 v16, v[80:81], s[8:9] offset:3584
	s_branch .LBB0_46
